# p2 conv XCD-local unit mapping: workgroups of one XCD take consecutive conv unit pairs so the 30-row halos shared with neighbours hit in that XCD's L2; on top of v8
# baseline (speedup 1.0000x reference)
; #define LAS __attribute__((address_space(3)))
; __device__ __forceinline__ float bflo(unsigned w) { return __uint_as_float(w << 16); }
; __device__ __forceinline__ float bfhi(unsigned w) { return __uint_as_float(w & 0xffff0000u); }
; __device__ __forceinline__ void conv_unit(LAS unsigned char* lds, int u, const bf16* PROJ, const float* conv_w, const float* conv_b, const float* ln_w, const float* ln_b, bf16* MIX, int tid, const WsRef& wsr) {
;     const int lane = tid & 63, wave = tid >> 6;
;     LAS float* U = (LAS float*)lds;
;     const int t0 = (u * 32) % SEQ; const size_t rowb = (size_t)(u * 32 / SEQ) * SEQ;
;     for (int it = tid; it < 62 * 64; it += 512) { const int r = it >> 6, cc = it & 63; const int t = t0 - 15 + r;
;         f32x4 u0 = (f32x4){0.f, 0.f, 0.f, 0.f}, u1 = u0;
;         if (t >= 0 && t < SEQ) { const bf16* pr = PROJ + (rowb + t) * INC + 2048 + cc * 8; const u32x4 a = *(const u32x4*)pr, g = *(const u32x4*)(pr + 512);
; #pragma unroll
;             for (int e = 0; e < 4; ++e) { const float a0 = bflo(a[e]), a1 = bfhi(a[e]), g0 = bflo(g[e]), g1 = bfhi(g[e]);
;                 const float v0 = a0 * __builtin_amdgcn_rcpf(1.f + __expf(-g0)), v1 = a1 * __builtin_amdgcn_rcpf(1.f + __expf(-g1));
;                 if (e < 2) { u0[2 * e] = v0; u0[2 * e + 1] = v1; } else { u1[2 * e - 4] = v0; u1[2 * e - 3] = v1; } } }
;         *(LAS f32x4*)(U + r * 512 + cc * 8) = u0; *(LAS f32x4*)(U + r * 512 + cc * 8 + 4) = u1; }
;     float w[31];
; #pragma unroll
;     for (int k = 0; k < 31; ++k) w[k] = conv_w[k * 512 + tid];
;     const float bias = conv_b[tid];
; __global__ void __launch_bounds__(512, 2) fwd_mega(Args a) {
;     ...
;         for (int u = bid; u < 512; u += G) conv_unit(lds, u, PROJ, a.in[9], a.in[10], a.in[11], a.in[12], MIX, tid, wsr);
.LBB0_219:
	v_mov_b32_e32 v9, 0
	v_lshlrev_b32_e32 v8, 2, v128
	v_lshl_add_u64 v[10:11], s[38:39], 0, v[8:9]
	s_mov_b64 s[8:9], 0x1800
	v_lshl_add_u64 v[14:15], v[10:11], 0, s[8:9]
	s_mov_b64 s[8:9], 0x2000
	s_waitcnt vmcnt(19)
	v_lshl_add_u64 v[16:17], v[10:11], 0, s[8:9]
	s_mov_b64 s[8:9], 0x2800
	v_lshl_add_u64 v[18:19], v[10:11], 0, s[8:9]
	s_mov_b64 s[8:9], 0x3000
	s_waitcnt vmcnt(18)
	v_lshl_add_u64 v[20:21], v[10:11], 0, s[8:9]
	s_mov_b64 s[8:9], 0x3800
	v_lshl_add_u64 v[22:23], v[10:11], 0, s[8:9]
	s_mov_b64 s[8:9], 0x4000
	v_and_b32_e32 v2, 0x1f8, v76
	s_waitcnt vmcnt(17)
	v_lshl_add_u64 v[24:25], v[10:11], 0, s[8:9]
	s_mov_b64 s[8:9], 0x4800
	v_lshl_add_u64 v[72:73], s[40:41], 0, v[8:9]
	v_add_u32_e32 v33, 0, v8
	v_lshlrev_b32_e32 v8, 2, v2
	v_lshl_add_u64 v[26:27], v[10:11], 0, s[8:9]
	s_mov_b64 s[8:9], 0x5000
	v_add_u32_e32 v3, 0, v8
	v_lshl_add_u64 v[76:77], s[42:43], 0, v[8:9]
	v_lshl_add_u64 v[78:79], s[44:45], 0, v[8:9]
	v_mbcnt_lo_u32_b32 v8, -1, 0
	s_waitcnt vmcnt(16)
	v_lshl_add_u64 v[28:29], v[10:11], 0, s[8:9]
	s_mov_b64 s[8:9], 0x5800
	v_mbcnt_hi_u32_b32 v8, -1, v8
	v_lshl_add_u64 v[30:31], v[10:11], 0, s[8:9]
	s_mov_b64 s[8:9], 0x6000
	v_and_b32_e32 v84, 64, v8
	v_lshl_add_u64 v[34:35], v[10:11], 0, s[8:9]
	s_mov_b64 s[8:9], 0x6800
	v_add_u32_e32 v84, 64, v84
	v_xor_b32_e32 v88, 1, v8
	v_lshl_add_u64 v[36:37], v[10:11], 0, s[8:9]
	s_mov_b64 s[8:9], 0x7000
	v_cmp_lt_i32_e32 vcc, v88, v84
	v_lshl_add_u64 v[38:39], v[10:11], 0, s[8:9]
	s_mov_b64 s[8:9], 0x7800
	v_cndmask_b32_e32 v88, v8, v88, vcc
	v_lshl_add_u64 v[40:41], v[10:11], 0, s[8:9]
	s_mov_b64 s[8:9], 0x8000
	v_lshlrev_b32_e32 v141, 2, v88
	v_xor_b32_e32 v88, 2, v8
	v_lshl_add_u64 v[42:43], v[10:11], 0, s[8:9]
	s_mov_b64 s[8:9], 0x8800
	v_cmp_lt_i32_e32 vcc, v88, v84
	v_lshl_add_u64 v[44:45], v[10:11], 0, s[8:9]
	s_mov_b64 s[8:9], 0x9000
	v_cndmask_b32_e32 v88, v8, v88, vcc
	v_lshl_add_u64 v[46:47], v[10:11], 0, s[8:9]
	s_mov_b64 s[8:9], 0x9800
	v_lshlrev_b32_e32 v205, 2, v88
	v_xor_b32_e32 v88, 4, v8
	v_lshl_add_u64 v[48:49], v[10:11], 0, s[8:9]
	s_mov_b64 s[8:9], 0xa000
	v_cmp_lt_i32_e32 vcc, v88, v84
	v_lshl_add_u64 v[50:51], v[10:11], 0, s[8:9]
	s_mov_b64 s[8:9], 0xa800
	v_cndmask_b32_e32 v88, v8, v88, vcc
	v_lshl_add_u64 v[52:53], v[10:11], 0, s[8:9]
	s_mov_b64 s[8:9], 0xb000
	v_lshlrev_b32_e32 v206, 2, v88
	v_xor_b32_e32 v88, 8, v8
	v_lshl_add_u64 v[54:55], v[10:11], 0, s[8:9]
	s_mov_b64 s[8:9], 0xb800
	v_cmp_lt_i32_e32 vcc, v88, v84
	v_lshl_add_u64 v[56:57], v[10:11], 0, s[8:9]
	s_mov_b64 s[8:9], 0xc000
	v_cndmask_b32_e32 v88, v8, v88, vcc
	v_lshl_add_u64 v[58:59], v[10:11], 0, s[8:9]
	s_mov_b64 s[8:9], 0xc800
	v_lshlrev_b32_e32 v207, 2, v88
	v_xor_b32_e32 v88, 16, v8
	v_lshl_add_u64 v[60:61], v[10:11], 0, s[8:9]
	s_mov_b64 s[8:9], 0xd000
	v_cmp_lt_i32_e32 vcc, v88, v84
	v_lshl_add_u64 v[62:63], v[10:11], 0, s[8:9]
	s_mov_b64 s[8:9], 0xd800
	v_cndmask_b32_e32 v88, v8, v88, vcc
	v_lshl_add_u64 v[64:65], v[10:11], 0, s[8:9]
	s_mov_b64 s[8:9], 0xe000
	v_and_b32_e32 v74, 60, v32
	v_lshlrev_b32_e32 v208, 2, v88
	v_xor_b32_e32 v88, 32, v8
	v_lshl_add_u64 v[66:67], v[10:11], 0, s[8:9]
	s_mov_b64 s[8:9], 0xe800
	v_or_b32_e32 v80, 1, v74
	v_or_b32_e32 v82, 2, v74
	v_or_b32_e32 v32, 3, v32
	v_cmp_lt_i32_e32 vcc, v88, v84
	v_lshlrev_b32_e32 v0, 3, v204
	v_lshlrev_b32_e32 v1, 5, v204
	s_mov_b64 s[4:5], 0x1000
	v_lshl_add_u64 v[68:69], v[10:11], 0, s[8:9]
	s_mov_b64 s[8:9], 0xf000
	v_lshlrev_b32_e32 v4, 11, v74
	v_lshlrev_b32_e32 v5, 11, v80
	v_lshlrev_b32_e32 v6, 11, v82
	v_lshlrev_b32_e32 v7, 11, v32
	v_cndmask_b32_e32 v8, v8, v88, vcc
	v_lshl_add_u64 v[12:13], v[10:11], 0, s[4:5]
	v_lshl_add_u64 v[70:71], v[10:11], 0, s[8:9]
	v_add_u32_e32 v81, 0x10000, v33
	v_add_u32_e32 v83, 0x10800, v33
	v_add_u32_e32 v85, 0x11000, v33
	v_add_u32_e32 v87, 0x11800, v33
	v_add_u32_e32 v89, 0x12000, v33
	v_add_u32_e32 v91, 0x12800, v33
	v_add_u32_e32 v93, 0x13000, v33
	v_add_u32_e32 v95, 0x13800, v33
	v_add_u32_e32 v97, 0x14000, v33
	v_add_u32_e32 v99, 0x14800, v33
	v_add_u32_e32 v101, 0x15000, v33
	v_add_u32_e32 v103, 0x15800, v33
	v_add_u32_e32 v105, 0x16000, v33
	v_add_u32_e32 v107, 0x16800, v33
	v_add_u32_e32 v109, 0x17000, v33
	v_add_u32_e32 v111, 0x17800, v33
	v_add_u32_e32 v113, 0x18000, v33
	v_add_u32_e32 v115, 0x18800, v33
	v_add_u32_e32 v117, 0x19000, v33
	v_add_u32_e32 v119, 0x19800, v33
	v_add_u32_e32 v121, 0x1a000, v33
	v_add_u32_e32 v123, 0x1a800, v33
	v_add_u32_e32 v125, 0x1b000, v33
	v_add_u32_e32 v127, 0x1b800, v33
	v_add_u32_e32 v129, 0x1c000, v33
	v_add_u32_e32 v131, 0x1c800, v33
	v_add_u32_e32 v133, 0x1d000, v33
	v_add_u32_e32 v135, 0x1d800, v33
	v_add_u32_e32 v137, 0x1e000, v33
	v_add_u32_e32 v139, 0x1e800, v33
	v_lshlrev_b32_e32 v209, 2, v8
	v_add_u32_e32 v210, 0xfffffe00, v128
	v_add3_u32 v211, v86, v1, 0
	v_add_u32_e32 v75, -15, v75
	s_movk_i32 s24, 0x2000
	s_movk_i32 s25, 0x1800
	v_lshlrev_b32_e32 v8, 1, v0
	s_movk_i32 s26, 0xd7f
	v_add_u32_e32 v212, v3, v4
	v_mov_b32_e32 v213, 0x358637bd
	s_mov_b32 s27, 0x800000
	v_lshlrev_b32_e32 v214, 1, v2
	v_add_u32_e32 v215, v3, v5
	v_add_u32_e32 v216, v3, v6
	v_add_u32_e32 v217, v3, v7
	v_mov_b32_e32 v218, 0x1800
	s_mov_b32 s88, s84
	s_and_b32 s28, s2, 7
	s_lshl_b32 s28, s28, 5
	s_lshr_b32 s3, s2, 3
	s_or_b32 s28, s28, s3
	s_lshl_b32 s28, s28, 1
	s_branch .LBB0_221
